# QKV epilogue: the four q/k norm-gain loads issued together behind one wait instead of four serial load+vmcnt(0) round trips
# baseline (speedup 1.0000x reference)
;     __device__ __forceinline__ void operator()(const f32x4 (&acc)[2][2][4][2], const Unit& u, int wr, int wc, int fr, int fq, const LAS float* rt) const {
;         const int row0 = u.pm * 256 + wr * 64 + fr, kind = u.pn >> 2;
;         f32x4 gv[2][2];
; #pragma unroll
;         for (int bj = 0; bj < 2; ++bj)
; #pragma unroll
;             for (int n = 0; n < 2; ++n) {
;                 if (kind < 2) { const float* gp = (kind == 0 ? qg : kg) + 32 * bj + 8 * fq + 4 * n; const float sc = kind == 0 ? 0.125f * LOG2E : 1.f; gv[bj][n] = gld<f32x4>(gp) * sc; }
;                 else gv[bj][n] = (f32x4){1.f, 1.f, 1.f, 1.f};
;             }
.LBB0_166:
	s_ashr_i32 s24, s4, 2
	s_cmp_lt_i32 s24, 2
	s_cselect_b64 s[42:43], -1, 0
	s_cmp_lt_u32 s4, 4
	s_cselect_b64 s[0:1], -1, 0
	v_mov_b32_e32 v143, 0x3e38aa3b
	v_cndmask_b32_e64 v158, 1.0, v143, s[0:1]
	v_lshrrev_b32_e32 v143, 1, v160
	v_and_b32_e32 v163, 24, v143
	s_cmp_gt_i32 s24, 1
	v_mov_b32_e32 v142, 1.0
	v_mov_b32_e32 v159, v158
	v_lshlrev_b32_e32 v162, 2, v163
	v_mov_b32_e32 v144, 1.0
	v_mov_b32_e32 v145, 1.0
	v_mov_b32_e32 v146, 1.0
	v_mov_b32_e32 v147, 1.0
	s_cbranch_scc1 .LBB0_168
	s_and_b64 s[8:9], s[0:1], exec
	s_cselect_b32 s9, s38, s6
	s_cselect_b32 s8, s97, s31
	global_load_dwordx4 v[144:147], v162, s[8:9]
	global_load_dwordx4 v[168:171], v162, s[8:9] offset:16
	global_load_dwordx4 v[152:155], v162, s[8:9] offset:128
	global_load_dwordx4 v[164:167], v162, s[8:9] offset:144
	v_cndmask_b32_e64 v143, 0, 1, s[42:43]
	v_cmp_ne_u32_e64 s[44:45], 1, v143
	s_waitcnt vmcnt(0)
	v_pk_mul_f32 v[146:147], v[158:159], v[146:147]
	v_pk_mul_f32 v[144:145], v[158:159], v[144:145]
	v_pk_mul_f32 v[148:149], v[158:159], v[170:171]
	v_pk_mul_f32 v[142:143], v[158:159], v[168:169]
	v_pk_mul_f32 v[154:155], v[158:159], v[154:155]
	v_pk_mul_f32 v[152:153], v[158:159], v[152:153]
	v_pk_mul_f32 v[156:157], v[158:159], v[166:167]
	v_pk_mul_f32 v[150:151], v[158:159], v[164:165]
	s_branch .LBB0_174
